# NA attention: branch-free bias and window mask for the 64 window scores per round (batched bias reads, v_cndmask instead of 64 exec-masked blocks)
# speedup vs baseline: 1.0088x; 1.0088x over previous
.LBB0_1566:
	s_add_i32 s0, s6, s7
	v_sub_co_u32_e64 v0, s[0:1], s0, 4
	v_mov_b32_e32 v46, v148
	v_mov_b32_e32 v64, v146
	v_min_u32_e32 v0, 0x78, v0
	v_cndmask_b32_e64 v47, v0, 0, s[0:1]
	v_add_u32_e32 v68, 0x200, v64
	v_add_u32_e32 v72, 0x400, v64
	v_add_u32_e32 v76, 0x600, v64
	v_lshlrev_b32_e32 v65, 6, v47
	v_lshlrev_b32_e32 v0, 4, v64
	v_ashrrev_i32_e32 v37, 3, v64
	v_ashrrev_i32_e32 v40, 3, v68
	v_ashrrev_i32_e32 v42, 3, v72
	v_ashrrev_i32_e32 v44, 3, v76
	v_and_b32_e32 v80, 0x70, v0
	v_add_u32_e32 v0, v65, v37
	v_add_u32_e32 v2, v65, v40
	v_add_u32_e32 v8, v65, v42
	v_add_u32_e32 v10, v65, v44
	v_add_u32_e32 v114, 0x800, v64
	v_add_u32_e32 v112, 0xa00, v64
	v_ashrrev_i32_e32 v1, 31, v0
	v_ashrrev_i32_e32 v3, 31, v2
	v_ashrrev_i32_e32 v9, 31, v8
	v_ashrrev_i32_e32 v11, 31, v10
	v_ashrrev_i32_e32 v48, 3, v114
	v_ashrrev_i32_e32 v49, 3, v112
	v_lshl_add_u64 v[32:33], s[46:47], 0, v[80:81]
	v_lshlrev_b64 v[0:1], 11, v[0:1]
	v_lshlrev_b64 v[2:3], 11, v[2:3]
	v_lshlrev_b64 v[8:9], 11, v[8:9]
	v_lshlrev_b64 v[10:11], 11, v[10:11]
	v_add_u32_e32 v16, v65, v48
	v_add_u32_e32 v18, v65, v49
	v_add_u32_e32 v110, 0xc00, v64
	v_add_u32_e32 v108, 0xe00, v64
	v_lshl_add_u64 v[0:1], v[32:33], 0, v[0:1]
	v_lshl_add_u64 v[4:5], v[32:33], 0, v[2:3]
	v_lshl_add_u64 v[8:9], v[32:33], 0, v[8:9]
	v_lshl_add_u64 v[12:13], v[32:33], 0, v[10:11]
	v_ashrrev_i32_e32 v17, 31, v16
	v_ashrrev_i32_e32 v19, 31, v18
	v_ashrrev_i32_e32 v50, 3, v110
	v_ashrrev_i32_e32 v51, 3, v108
	v_add_u32_e32 v106, 0x1000, v64
	global_load_dwordx4 v[0:3], v[0:1], off
	s_nop 0
	global_load_dwordx4 v[4:7], v[4:5], off
	s_nop 0
	global_load_dwordx4 v[8:11], v[8:9], off
	s_nop 0
	global_load_dwordx4 v[12:15], v[12:13], off
	v_lshlrev_b64 v[16:17], 11, v[16:17]
	v_lshlrev_b64 v[18:19], 11, v[18:19]
	v_add_u32_e32 v24, v65, v50
	v_add_u32_e32 v26, v65, v51
	v_ashrrev_i32_e32 v52, 3, v106
	v_lshl_add_u64 v[16:17], v[32:33], 0, v[16:17]
	v_lshl_add_u64 v[20:21], v[32:33], 0, v[18:19]
	v_ashrrev_i32_e32 v25, 31, v24
	v_ashrrev_i32_e32 v27, 31, v26
	v_add_u32_e32 v34, v65, v52
	global_load_dwordx4 v[16:19], v[16:17], off
	s_nop 0
	global_load_dwordx4 v[20:23], v[20:21], off
	v_lshlrev_b64 v[24:25], 11, v[24:25]
	v_lshlrev_b64 v[26:27], 11, v[26:27]
	v_ashrrev_i32_e32 v35, 31, v34
	v_lshl_add_u64 v[24:25], v[32:33], 0, v[24:25]
	v_lshl_add_u64 v[28:29], v[32:33], 0, v[26:27]
	v_lshlrev_b64 v[34:35], 11, v[34:35]
	global_load_dwordx4 v[24:27], v[24:25], off
	s_nop 0
	global_load_dwordx4 v[28:31], v[28:29], off
	v_lshl_add_u64 v[32:33], v[32:33], 0, v[34:35]
	global_load_dwordx4 v[32:35], v[32:33], off
	v_or_b32_e32 v36, 0x11b80, v80
	v_mad_u64_u32 v[38:39], s[0:1], v37, s40, v[36:37]
	v_mad_u64_u32 v[40:41], s[0:1], v40, s40, v[36:37]
	v_mad_u64_u32 v[42:43], s[0:1], v42, s40, v[36:37]
	v_mad_u64_u32 v[44:45], s[0:1], v44, s40, v[36:37]
	s_waitcnt lgkmcnt(0)
	s_barrier
	v_and_b32_e32 v103, 15, v46
	v_add_u32_e32 v80, v99, v103
	v_ashrrev_i32_e32 v54, 4, v46
	v_lshlrev_b32_e32 v104, 3, v54
	v_ashrrev_i32_e32 v105, 31, v104
	v_or_b32_e32 v53, v103, v89
	v_lshlrev_b32_e32 v102, 2, v54
	s_waitcnt vmcnt(8)
	ds_write_b128 v38, v[0:3]
	s_waitcnt vmcnt(7)
	ds_write_b128 v40, v[4:7]
	s_waitcnt vmcnt(6)
	ds_write_b128 v42, v[8:11]
	s_waitcnt vmcnt(5)
	ds_write_b128 v44, v[12:15]
	v_mad_u64_u32 v[0:1], s[0:1], v48, s40, v[36:37]
	v_add_u32_e32 v8, s7, v159
	v_subrev_co_u32_e32 v8, vcc, 4, v8
	v_min_u32_e32 v8, 0x78, v8
	s_nop 0
	v_cndmask_b32_e64 v8, v8, 0, vcc
	v_add_u32_e32 v10, v103, v93
	v_sub_u32_e32 v161, v8, v47
	s_waitcnt vmcnt(4)
	ds_write_b128 v0, v[16:19]
	v_mad_u64_u32 v[0:1], s[0:1], v49, s40, v[36:37]
	s_waitcnt vmcnt(3)
	ds_write_b128 v0, v[20:23]
	v_mad_u64_u32 v[0:1], s[0:1], v50, s40, v[36:37]
	v_lshl_add_u32 v10, v161, 6, v10
	s_waitcnt vmcnt(2)
	ds_write_b128 v0, v[24:27]
	v_mad_u64_u32 v[0:1], s[0:1], v51, s40, v[36:37]
	s_waitcnt vmcnt(1)
	ds_write_b128 v0, v[28:31]
	v_mad_u64_u32 v[0:1], s[0:1], v52, s40, v[36:37]
	v_lshl_add_u64 v[36:37], s[42:43], 0, v[80:81]
	s_waitcnt vmcnt(0)
	ds_write_b128 v0, v[32:35]
	v_lshlrev_b64 v[0:1], 11, v[36:37]
	v_lshl_add_u64 v[0:1], s[48:49], 0, v[0:1]
	v_lshl_add_u64 v[0:1], v[104:105], 1, v[0:1]
	s_waitcnt lgkmcnt(0)
	s_barrier
	global_load_dwordx4 v[4:7], v[0:1], off
	s_nop 0
	global_load_dwordx4 v[0:3], v[0:1], off offset:64
	v_and_b32_e32 v9, -16, v46
	v_subrev_co_u32_e32 v11, vcc, 8, v53
	v_add_u32_e32 v8, v8, v101
	s_movk_i32 s0, 0x7c
	v_mad_i32_i24 v56, v10, s40, v95
	v_min_u32_e32 v11, 48, v11
	v_mul_lo_u32 v8, v8, s0
	v_add_u32_e32 v55, v56, v9
	v_cndmask_b32_e64 v57, v11, 0, vcc
	v_add_u32_e32 v38, 0x11400, v8
	v_mov_b32_e32 v39, v55
	ds_read_b128 v[16:19], v39 offset:9216
	ds_read_b128 v[24:27], v39 offset:2304
	ds_read_b128 v[32:35], v39
	ds_read_b128 v[8:11], v39 offset:11520
	ds_read_b128 v[12:15], v39 offset:11584
	ds_read_b128 v[20:23], v39 offset:9280
	ds_read_b128 v[28:31], v39 offset:2368
	ds_read_b128 v[58:61], v39 offset:64
	v_add_u32_e32 v54, v102, v93
	v_add_u32_e32 v224, 16, v57
	v_cmp_ge_i32_e32 vcc, v54, v57
	v_cmp_lt_i32_e64 s[4:5], v54, v224
	v_sub_u32_e32 v223, v54, v53
	v_add_u32_e32 v223, 15, v223
	s_and_b64 s[54:55], vcc, s[4:5]
	v_med3_i32 v223, v223, 0, 30
	v_lshl_add_u32 v214, v223, 2, v38
	v_add_u32_e32 v222, 1, v54
	v_cmp_ge_i32_e32 vcc, v222, v57
	v_cmp_lt_i32_e64 s[4:5], v222, v224
	v_sub_u32_e32 v223, v222, v53
	v_add_u32_e32 v223, 15, v223
	s_and_b64 s[64:65], vcc, s[4:5]
	v_med3_i32 v223, v223, 0, 30
	v_lshl_add_u32 v215, v223, 2, v38
	v_add_u32_e32 v222, 2, v54
	v_cmp_ge_i32_e32 vcc, v222, v57
	v_cmp_lt_i32_e64 s[4:5], v222, v224
	v_sub_u32_e32 v223, v222, v53
	v_add_u32_e32 v223, 15, v223
	s_and_b64 s[74:75], vcc, s[4:5]
	v_med3_i32 v223, v223, 0, 30
	v_lshl_add_u32 v216, v223, 2, v38
	v_add_u32_e32 v222, 3, v54
	v_cmp_ge_i32_e32 vcc, v222, v57
	v_cmp_lt_i32_e64 s[4:5], v222, v224
	v_sub_u32_e32 v223, v222, v53
	v_add_u32_e32 v223, 15, v223
	s_and_b64 s[80:81], vcc, s[4:5]
	v_med3_i32 v223, v223, 0, 30
	v_lshl_add_u32 v217, v223, 2, v38
	v_add_u32_e32 v222, 16, v54
	v_cmp_ge_i32_e32 vcc, v222, v57
	v_cmp_lt_i32_e64 s[4:5], v222, v224
	v_sub_u32_e32 v223, v222, v53
	v_add_u32_e32 v223, 15, v223
	s_and_b64 s[86:87], vcc, s[4:5]
	v_med3_i32 v223, v223, 0, 30
	v_lshl_add_u32 v218, v223, 2, v38
	v_add_u32_e32 v222, 17, v54
	v_cmp_ge_i32_e32 vcc, v222, v57
	v_cmp_lt_i32_e64 s[4:5], v222, v224
	v_sub_u32_e32 v223, v222, v53
	v_add_u32_e32 v223, 15, v223
	s_and_b64 s[90:91], vcc, s[4:5]
	v_med3_i32 v223, v223, 0, 30
	v_lshl_add_u32 v219, v223, 2, v38
	v_add_u32_e32 v222, 18, v54
	v_cmp_ge_i32_e32 vcc, v222, v57
	v_cmp_lt_i32_e64 s[4:5], v222, v224
	v_sub_u32_e32 v223, v222, v53
	v_add_u32_e32 v223, 15, v223
	s_and_b64 s[24:25], vcc, s[4:5]
	v_med3_i32 v223, v223, 0, 30
	v_lshl_add_u32 v220, v223, 2, v38
	v_add_u32_e32 v222, 19, v54
	v_cmp_ge_i32_e32 vcc, v222, v57
	v_cmp_lt_i32_e64 s[4:5], v222, v224
	v_sub_u32_e32 v223, v222, v53
	v_add_u32_e32 v223, 15, v223
	s_and_b64 s[0:1], vcc, s[4:5]
	v_med3_i32 v223, v223, 0, 30
	v_lshl_add_u32 v221, v223, 2, v38
	v_mov_b32_e32 v57, 0xf149f2ca
	ds_read_b32 v222, v214 offset:868
	ds_read_b32 v223, v215 offset:868
	ds_read_b32 v224, v216 offset:868
	ds_read_b32 v225, v217 offset:868
	ds_read_b32 v226, v218 offset:868
	ds_read_b32 v227, v219 offset:868
	ds_read_b32 v228, v220 offset:868
	ds_read_b32 v229, v221 offset:868
	ds_read_b32 v230, v214 offset:992
	ds_read_b32 v231, v215 offset:992
	ds_read_b32 v232, v216 offset:992
	ds_read_b32 v233, v217 offset:992
	ds_read_b32 v234, v218 offset:992
	ds_read_b32 v235, v219 offset:992
	ds_read_b32 v236, v220 offset:992
	ds_read_b32 v237, v221 offset:992
	s_waitcnt vmcnt(0)
	s_waitcnt lgkmcnt(15)
	v_mfma_f32_16x16x32_bf16 v[40:43], v[32:35], v[4:7], 0
	v_mfma_f32_16x16x32_bf16 v[44:47], v[24:27], v[4:7], 0
	v_mfma_f32_16x16x32_bf16 v[48:51], v[16:19], v[4:7], 0
	v_mfma_f32_16x16x32_bf16 v[52:55], v[8:11], v[4:7], 0
	v_mfma_f32_16x16x32_bf16 v[40:43], v[58:61], v[0:3], v[40:43]
	v_mfma_f32_16x16x32_bf16 v[44:47], v[28:31], v[0:3], v[44:47]
	v_mfma_f32_16x16x32_bf16 v[48:51], v[20:23], v[0:3], v[48:51]
	v_mfma_f32_16x16x32_bf16 v[52:55], v[12:15], v[0:3], v[52:55]
	ds_read_b128 v[16:19], v39 offset:27648
	ds_read_b128 v[24:27], v39 offset:20736
	ds_read_b128 v[32:35], v39 offset:18432
	ds_read_b128 v[8:11], v39 offset:29952
	ds_read_b128 v[12:15], v39 offset:30016
	ds_read_b128 v[20:23], v39 offset:27712
	ds_read_b128 v[28:31], v39 offset:20800
	ds_read_b128 v[58:61], v39 offset:18496
	s_waitcnt lgkmcnt(8)
	s_nop 3
	v_add_f32_e32 v222, v40, v222
	v_mul_f32_e32 v222, 0x3fb8aa3b, v222
	v_cndmask_b32_e64 v73, v57, v222, s[54:55]
	v_add_f32_e32 v223, v41, v223
	v_mul_f32_e32 v223, 0x3fb8aa3b, v223
	v_cndmask_b32_e64 v69, v57, v223, s[64:65]
	v_add_f32_e32 v224, v42, v224
	v_mul_f32_e32 v224, 0x3fb8aa3b, v224
	v_cndmask_b32_e64 v75, v57, v224, s[74:75]
	v_add_f32_e32 v225, v43, v225
	v_mul_f32_e32 v225, 0x3fb8aa3b, v225
	v_cndmask_b32_e64 v74, v57, v225, s[80:81]
	v_add_f32_e32 v226, v44, v226
	v_mul_f32_e32 v226, 0x3fb8aa3b, v226
	v_cndmask_b32_e64 v78, v57, v226, s[86:87]
	v_add_f32_e32 v227, v45, v227
	v_mul_f32_e32 v227, 0x3fb8aa3b, v227
	v_cndmask_b32_e64 v77, v57, v227, s[90:91]
	v_add_f32_e32 v228, v46, v228
	v_mul_f32_e32 v228, 0x3fb8aa3b, v228
	v_cndmask_b32_e64 v80, v57, v228, s[24:25]
	v_add_f32_e32 v229, v47, v229
	v_mul_f32_e32 v229, 0x3fb8aa3b, v229
	v_cndmask_b32_e64 v79, v57, v229, s[0:1]
	v_add_f32_e32 v230, v48, v230
	v_mul_f32_e32 v230, 0x3fb8aa3b, v230
	v_cndmask_b32_e64 v118, v57, v230, s[54:55]
	v_add_f32_e32 v231, v49, v231
	v_mul_f32_e32 v231, 0x3fb8aa3b, v231
	v_cndmask_b32_e64 v115, v57, v231, s[64:65]
	v_add_f32_e32 v232, v50, v232
	v_mul_f32_e32 v232, 0x3fb8aa3b, v232
	v_cndmask_b32_e64 v120, v57, v232, s[74:75]
	v_add_f32_e32 v233, v51, v233
	v_mul_f32_e32 v233, 0x3fb8aa3b, v233
	v_cndmask_b32_e64 v119, v57, v233, s[80:81]
	v_add_f32_e32 v234, v52, v234
	v_mul_f32_e32 v234, 0x3fb8aa3b, v234
	v_cndmask_b32_e64 v122, v57, v234, s[86:87]
	v_add_f32_e32 v235, v53, v235
	v_mul_f32_e32 v235, 0x3fb8aa3b, v235
	v_cndmask_b32_e64 v121, v57, v235, s[90:91]
	v_add_f32_e32 v236, v54, v236
	v_mul_f32_e32 v236, 0x3fb8aa3b, v236
	v_cndmask_b32_e64 v124, v57, v236, s[24:25]
	v_add_f32_e32 v237, v55, v237
	v_mul_f32_e32 v237, 0x3fb8aa3b, v237
	v_cndmask_b32_e64 v123, v57, v237, s[0:1]
	ds_read_b32 v222, v214 offset:1116
	ds_read_b32 v223, v215 offset:1116
	ds_read_b32 v224, v216 offset:1116
	ds_read_b32 v225, v217 offset:1116
	ds_read_b32 v226, v218 offset:1116
	ds_read_b32 v227, v219 offset:1116
	ds_read_b32 v228, v220 offset:1116
	ds_read_b32 v229, v221 offset:1116
	ds_read_b32 v230, v214 offset:1240
	ds_read_b32 v231, v215 offset:1240
	ds_read_b32 v232, v216 offset:1240
	ds_read_b32 v233, v217 offset:1240
	ds_read_b32 v234, v218 offset:1240
	ds_read_b32 v235, v219 offset:1240
	ds_read_b32 v236, v220 offset:1240
	ds_read_b32 v237, v221 offset:1240
	s_waitcnt lgkmcnt(15)
	v_mfma_f32_16x16x32_bf16 v[40:43], v[32:35], v[4:7], 0
	v_mfma_f32_16x16x32_bf16 v[44:47], v[24:27], v[4:7], 0
	v_mfma_f32_16x16x32_bf16 v[48:51], v[16:19], v[4:7], 0
	v_mfma_f32_16x16x32_bf16 v[52:55], v[8:11], v[4:7], 0
	v_mfma_f32_16x16x32_bf16 v[40:43], v[58:61], v[0:3], v[40:43]
	v_mfma_f32_16x16x32_bf16 v[44:47], v[28:31], v[0:3], v[44:47]
	v_mfma_f32_16x16x32_bf16 v[48:51], v[20:23], v[0:3], v[48:51]
	v_mfma_f32_16x16x32_bf16 v[52:55], v[12:15], v[0:3], v[52:55]
	ds_read_b128 v[16:19], v39 offset:46080
	ds_read_b128 v[24:27], v39 offset:39168
	ds_read_b128 v[32:35], v39 offset:36864
	ds_read_b128 v[8:11], v39 offset:48384
	ds_read_b128 v[12:15], v39 offset:48448
	ds_read_b128 v[20:23], v39 offset:46144
	ds_read_b128 v[28:31], v39 offset:39232
	ds_read_b128 v[58:61], v39 offset:36928
	s_waitcnt lgkmcnt(8)
	s_nop 3
	v_add_f32_e32 v222, v40, v222
	v_mul_f32_e32 v222, 0x3fb8aa3b, v222
	v_cndmask_b32_e64 v162, v57, v222, s[54:55]
	v_add_f32_e32 v223, v41, v223
	v_mul_f32_e32 v223, 0x3fb8aa3b, v223
	v_cndmask_b32_e64 v125, v57, v223, s[64:65]
	v_add_f32_e32 v224, v42, v224
	v_mul_f32_e32 v224, 0x3fb8aa3b, v224
	v_cndmask_b32_e64 v164, v57, v224, s[74:75]
	v_add_f32_e32 v225, v43, v225
	v_mul_f32_e32 v225, 0x3fb8aa3b, v225
	v_cndmask_b32_e64 v163, v57, v225, s[80:81]
	v_add_f32_e32 v226, v44, v226
	v_mul_f32_e32 v226, 0x3fb8aa3b, v226
	v_cndmask_b32_e64 v166, v57, v226, s[86:87]
	v_add_f32_e32 v227, v45, v227
	v_mul_f32_e32 v227, 0x3fb8aa3b, v227
	v_cndmask_b32_e64 v165, v57, v227, s[90:91]
	v_add_f32_e32 v228, v46, v228
	v_mul_f32_e32 v228, 0x3fb8aa3b, v228
	v_cndmask_b32_e64 v168, v57, v228, s[24:25]
	v_add_f32_e32 v229, v47, v229
	v_mul_f32_e32 v229, 0x3fb8aa3b, v229
	v_cndmask_b32_e64 v167, v57, v229, s[0:1]
	v_add_f32_e32 v230, v48, v230
	v_mul_f32_e32 v230, 0x3fb8aa3b, v230
	v_cndmask_b32_e64 v170, v57, v230, s[54:55]
	v_add_f32_e32 v231, v49, v231
	v_mul_f32_e32 v231, 0x3fb8aa3b, v231
	v_cndmask_b32_e64 v169, v57, v231, s[64:65]
	v_add_f32_e32 v232, v50, v232
	v_mul_f32_e32 v232, 0x3fb8aa3b, v232
	v_cndmask_b32_e64 v172, v57, v232, s[74:75]
	v_add_f32_e32 v233, v51, v233
	v_mul_f32_e32 v233, 0x3fb8aa3b, v233
	v_cndmask_b32_e64 v171, v57, v233, s[80:81]
	v_add_f32_e32 v234, v52, v234
	v_mul_f32_e32 v234, 0x3fb8aa3b, v234
	v_cndmask_b32_e64 v174, v57, v234, s[86:87]
	v_add_f32_e32 v235, v53, v235
	v_mul_f32_e32 v235, 0x3fb8aa3b, v235
	v_cndmask_b32_e64 v173, v57, v235, s[90:91]
	v_add_f32_e32 v236, v54, v236
	v_mul_f32_e32 v236, 0x3fb8aa3b, v236
	v_cndmask_b32_e64 v176, v57, v236, s[24:25]
	v_add_f32_e32 v237, v55, v237
	v_mul_f32_e32 v237, 0x3fb8aa3b, v237
	v_cndmask_b32_e64 v175, v57, v237, s[0:1]
	ds_read_b32 v222, v214 offset:1364
	ds_read_b32 v223, v215 offset:1364
	ds_read_b32 v224, v216 offset:1364
	ds_read_b32 v225, v217 offset:1364
	ds_read_b32 v226, v218 offset:1364
	ds_read_b32 v227, v219 offset:1364
	ds_read_b32 v228, v220 offset:1364
	ds_read_b32 v229, v221 offset:1364
	ds_read_b32 v230, v214 offset:1488
	ds_read_b32 v231, v215 offset:1488
	ds_read_b32 v232, v216 offset:1488
	ds_read_b32 v233, v217 offset:1488
	ds_read_b32 v234, v218 offset:1488
	ds_read_b32 v235, v219 offset:1488
	ds_read_b32 v236, v220 offset:1488
	ds_read_b32 v237, v221 offset:1488
	s_waitcnt lgkmcnt(15)
	v_mfma_f32_16x16x32_bf16 v[40:43], v[32:35], v[4:7], 0
	v_mfma_f32_16x16x32_bf16 v[44:47], v[24:27], v[4:7], 0
	v_mfma_f32_16x16x32_bf16 v[48:51], v[16:19], v[4:7], 0
	v_mfma_f32_16x16x32_bf16 v[52:55], v[8:11], v[4:7], 0
	v_mfma_f32_16x16x32_bf16 v[40:43], v[58:61], v[0:3], v[40:43]
	v_mfma_f32_16x16x32_bf16 v[44:47], v[28:31], v[0:3], v[44:47]
	v_mfma_f32_16x16x32_bf16 v[48:51], v[20:23], v[0:3], v[48:51]
	v_mfma_f32_16x16x32_bf16 v[52:55], v[12:15], v[0:3], v[52:55]
	ds_read_b128 v[16:19], v39 offset:64512
	ds_read_b128 v[24:27], v39 offset:57600
	ds_read_b128 v[32:35], v39 offset:55296
	ds_read_b128 v[20:23], v39 offset:64576
	ds_read_b128 v[28:31], v39 offset:57664
	ds_read_b128 v[58:61], v39 offset:55360
	v_add_u32_e32 v39, 0x10500, v39
	ds_read_b128 v[8:11], v39
	ds_read_b128 v[12:15], v39 offset:64
	s_waitcnt lgkmcnt(8)
	s_nop 3
	v_add_f32_e32 v222, v40, v222
	v_mul_f32_e32 v222, 0x3fb8aa3b, v222
	v_cndmask_b32_e64 v178, v57, v222, s[54:55]
	v_add_f32_e32 v223, v41, v223
	v_mul_f32_e32 v223, 0x3fb8aa3b, v223
	v_cndmask_b32_e64 v177, v57, v223, s[64:65]
	v_add_f32_e32 v224, v42, v224
	v_mul_f32_e32 v224, 0x3fb8aa3b, v224
	v_cndmask_b32_e64 v180, v57, v224, s[74:75]
	v_add_f32_e32 v225, v43, v225
	v_mul_f32_e32 v225, 0x3fb8aa3b, v225
	v_cndmask_b32_e64 v179, v57, v225, s[80:81]
	v_add_f32_e32 v226, v44, v226
	v_mul_f32_e32 v226, 0x3fb8aa3b, v226
	v_cndmask_b32_e64 v182, v57, v226, s[86:87]
	v_add_f32_e32 v227, v45, v227
	v_mul_f32_e32 v227, 0x3fb8aa3b, v227
	v_cndmask_b32_e64 v181, v57, v227, s[90:91]
	v_add_f32_e32 v228, v46, v228
	v_mul_f32_e32 v228, 0x3fb8aa3b, v228
	v_cndmask_b32_e64 v184, v57, v228, s[24:25]
	v_add_f32_e32 v229, v47, v229
	v_mul_f32_e32 v229, 0x3fb8aa3b, v229
	v_cndmask_b32_e64 v183, v57, v229, s[0:1]
	v_add_f32_e32 v230, v48, v230
	v_mul_f32_e32 v230, 0x3fb8aa3b, v230
	v_cndmask_b32_e64 v186, v57, v230, s[54:55]
	v_add_f32_e32 v231, v49, v231
	v_mul_f32_e32 v231, 0x3fb8aa3b, v231
	v_cndmask_b32_e64 v185, v57, v231, s[64:65]
	v_add_f32_e32 v232, v50, v232
	v_mul_f32_e32 v232, 0x3fb8aa3b, v232
	v_cndmask_b32_e64 v188, v57, v232, s[74:75]
	v_add_f32_e32 v233, v51, v233
	v_mul_f32_e32 v233, 0x3fb8aa3b, v233
	v_cndmask_b32_e64 v187, v57, v233, s[80:81]
	v_add_f32_e32 v234, v52, v234
	v_mul_f32_e32 v234, 0x3fb8aa3b, v234
	v_cndmask_b32_e64 v190, v57, v234, s[86:87]
	v_add_f32_e32 v235, v53, v235
	v_mul_f32_e32 v235, 0x3fb8aa3b, v235
	v_cndmask_b32_e64 v189, v57, v235, s[90:91]
	v_add_f32_e32 v236, v54, v236
	v_mul_f32_e32 v236, 0x3fb8aa3b, v236
	v_cndmask_b32_e64 v192, v57, v236, s[24:25]
	v_add_f32_e32 v237, v55, v237
	v_mul_f32_e32 v237, 0x3fb8aa3b, v237
	v_cndmask_b32_e64 v191, v57, v237, s[0:1]
	ds_read_b32 v222, v214 offset:1612
	ds_read_b32 v223, v215 offset:1612
	ds_read_b32 v224, v216 offset:1612
	ds_read_b32 v225, v217 offset:1612
	ds_read_b32 v226, v218 offset:1612
	ds_read_b32 v227, v219 offset:1612
	ds_read_b32 v228, v220 offset:1612
	ds_read_b32 v229, v221 offset:1612
	ds_read_b32 v230, v214 offset:1736
	ds_read_b32 v231, v215 offset:1736
	ds_read_b32 v232, v216 offset:1736
	ds_read_b32 v233, v217 offset:1736
	ds_read_b32 v234, v218 offset:1736
	ds_read_b32 v235, v219 offset:1736
	ds_read_b32 v236, v220 offset:1736
	ds_read_b32 v237, v221 offset:1736
	s_waitcnt lgkmcnt(15)
	v_mfma_f32_16x16x32_bf16 v[40:43], v[32:35], v[4:7], 0
	v_mfma_f32_16x16x32_bf16 v[44:47], v[24:27], v[4:7], 0
	v_mfma_f32_16x16x32_bf16 v[48:51], v[16:19], v[4:7], 0
	v_mfma_f32_16x16x32_bf16 v[52:55], v[8:11], v[4:7], 0
	v_mfma_f32_16x16x32_bf16 v[40:43], v[58:61], v[0:3], v[40:43]
	v_mfma_f32_16x16x32_bf16 v[44:47], v[28:31], v[0:3], v[44:47]
	v_mfma_f32_16x16x32_bf16 v[48:51], v[20:23], v[0:3], v[48:51]
	v_mfma_f32_16x16x32_bf16 v[52:55], v[12:15], v[0:3], v[52:55]
	s_waitcnt lgkmcnt(0)
	s_nop 7
	s_nop 3
	v_add_f32_e32 v222, v40, v222
	v_mul_f32_e32 v222, 0x3fb8aa3b, v222
	v_cndmask_b32_e64 v198, v57, v222, s[54:55]
	v_add_f32_e32 v223, v41, v223
	v_mul_f32_e32 v223, 0x3fb8aa3b, v223
	v_cndmask_b32_e64 v193, v57, v223, s[64:65]
	v_add_f32_e32 v224, v42, v224
	v_mul_f32_e32 v224, 0x3fb8aa3b, v224
	v_cndmask_b32_e64 v200, v57, v224, s[74:75]
	v_add_f32_e32 v225, v43, v225
	v_mul_f32_e32 v225, 0x3fb8aa3b, v225
	v_cndmask_b32_e64 v199, v57, v225, s[80:81]
	v_add_f32_e32 v226, v44, v226
	v_mul_f32_e32 v226, 0x3fb8aa3b, v226
	v_cndmask_b32_e64 v202, v57, v226, s[86:87]
	v_add_f32_e32 v227, v45, v227
	v_mul_f32_e32 v227, 0x3fb8aa3b, v227
	v_cndmask_b32_e64 v201, v57, v227, s[90:91]
	v_add_f32_e32 v228, v46, v228
	v_mul_f32_e32 v228, 0x3fb8aa3b, v228
	v_cndmask_b32_e64 v204, v57, v228, s[24:25]
	v_add_f32_e32 v229, v47, v229
	v_mul_f32_e32 v229, 0x3fb8aa3b, v229
	v_cndmask_b32_e64 v203, v57, v229, s[0:1]
	v_add_f32_e32 v230, v48, v230
	v_mul_f32_e32 v230, 0x3fb8aa3b, v230
	v_cndmask_b32_e64 v206, v57, v230, s[54:55]
	v_add_f32_e32 v231, v49, v231
	v_mul_f32_e32 v231, 0x3fb8aa3b, v231
	v_cndmask_b32_e64 v205, v57, v231, s[64:65]
	v_add_f32_e32 v232, v50, v232
	v_mul_f32_e32 v232, 0x3fb8aa3b, v232
	v_cndmask_b32_e64 v208, v57, v232, s[74:75]
	v_add_f32_e32 v233, v51, v233
	v_mul_f32_e32 v233, 0x3fb8aa3b, v233
	v_cndmask_b32_e64 v207, v57, v233, s[80:81]
	v_add_f32_e32 v234, v52, v234
	v_mul_f32_e32 v234, 0x3fb8aa3b, v234
	v_cndmask_b32_e64 v210, v57, v234, s[86:87]
	v_add_f32_e32 v235, v53, v235
	v_mul_f32_e32 v235, 0x3fb8aa3b, v235
	v_cndmask_b32_e64 v209, v57, v235, s[90:91]
	v_add_f32_e32 v236, v54, v236
	v_mul_f32_e32 v236, 0x3fb8aa3b, v236
	v_cndmask_b32_e64 v212, v57, v236, s[24:25]
	v_add_f32_e32 v237, v55, v237
	v_mul_f32_e32 v237, 0x3fb8aa3b, v237
	v_cndmask_b32_e64 v211, v57, v237, s[0:1]
	v_lshlrev_b32_e32 v57, 1, v104
	s_mov_b64 s[4:5], exec
	s_branch .LBB0_1565
